# attention work-queue ticket issued at the start of each unit's output epilogue (hidden round trip), ticket parked in v241 with its live value in spare LDS
# speedup vs baseline: 1.0163x; 1.0037x over previous
; #define LAS __attribute__((address_space(3)))
; __device__ __forceinline__ int opaque_tid() { int t = threadIdx.x; asm volatile("" : "+v"(t)); return t; }
; #define WSPTR() ({ unsigned char* w_ = ARGS().ws; asm volatile("" : "+s"(w_)); w_; })
; __global__ void __launch_bounds__(NWAVES * 64, 2) mega_fwd(Args args_) {
;     ...
;             { unsigned char* ws = WSPTR(); const int l = step / 3; const int tid = opaque_tid();
;               volatile LAS unsigned* MISC = (volatile LAS unsigned*)(ldsl + MISC_OFF);
;               volatile LAS int* T = (volatile LAS int*)(ldsl + MISC_OFF + 1024);
;               unsigned* qctr = (unsigned*)(ws + WS_CTL) + 64 * (1 + l);
;               const attn_body::bf16* QKV = (const attn_body::bf16*)(ws + WS_R1); attn_body::bf16* OBa = (attn_body::bf16*)(ws + WS_OB);
;               const int TC = T[772];
;               for (;;) {
;                   if (tid == 0) MISC[0] = atomicAdd(qctr, 1u);
;                   __syncthreads(); const int u = __builtin_amdgcn_readfirstlane((int)MISC[0]); __syncthreads();
.LBB0_1073:
	s_or_b64 exec, exec, s[0:1]
	s_mov_b64 s[0:1], s[84:85]
	s_waitcnt lgkmcnt(0)
	s_barrier
	s_load_dwordx2 s[16:17], s[0:1], 0xe0
	v_readlane_b32 s0, v254, 45
	s_lshl_b32 s0, s0, 2
	s_waitcnt lgkmcnt(0)
	s_add_u32 s18, s16, s0
	s_addc_u32 s19, s17, 0
	s_add_u32 s14, s16, 0x5c00000
	s_addc_u32 s15, s17, 0
	s_add_u32 s37, s16, 0x5c00600
	s_addc_u32 s38, s17, 0
	s_add_u32 s39, s16, 0x5c00800
	s_addc_u32 s42, s17, 0
	s_add_u32 s43, s16, 0x5c00900
	v_readlane_b32 s1, v254, 33
	s_addc_u32 s44, s17, 0
	s_add_u32 s45, s16, 0xb400200
	v_mov_b32_e32 v1, s1
	v_readlane_b32 s0, v254, 15
	s_addc_u32 s46, s17, 0
	v_readlane_b32 s1, v254, 16
	s_and_b64 s[0:1], s[0:1], exec
	s_cselect_b32 s47, 4, 0
	s_add_u32 s48, s16, 0xe400000
	s_addc_u32 s49, s17, 0
	s_add_u32 s50, s16, 0x800000
	s_addc_u32 s51, s17, 0
	s_add_u32 s52, s16, 0x5c00200
	s_addc_u32 s53, s17, 0
	s_add_u32 s54, s16, 0x5c00400
	s_addc_u32 s55, s17, 0
	s_add_u32 s56, s16, 0xfc00000
	s_addc_u32 s57, s17, 0
	s_add_u32 s58, s16, 0xfe00000
	s_addc_u32 s59, s17, 0
	v_mov_b32_e32 v0, v230
	s_add_u32 s60, s16, 0x5c00a00
	ds_read_b32 v1, v1
	s_addc_u32 s61, s17, 0
	s_add_u32 s62, s16, 0x5c00e00
	s_addc_u32 s63, s17, 0
	s_add_u32 s64, s16, 0x5c01200
	s_addc_u32 s65, s17, 0
	s_waitcnt lgkmcnt(0)
	v_readfirstlane_b32 s36, v1
	s_add_u32 s66, s16, 0xb400400
	v_cmp_eq_u32_e64 s[6:7], 0, v0
	v_add_u32_e32 v245, 0x400, v1
	v_add_u32_e32 v246, 0x500, v1
	s_addc_u32 s67, s17, 0
	s_sub_i32 s68, 0, s36
	v_mbcnt_lo_u32_b32 v0, -1, 0
	v_mbcnt_hi_u32_b32 v0, -1, v0
	v_lshlrev_b32_e32 v0, 2, v0
	v_lshl_add_u32 v0, s47, 6, v0
	s_load_dwordx2 s[0:1], s[84:85], 0x60
	s_waitcnt lgkmcnt(0)
	global_load_dword v1, v0, s[0:1]
	s_load_dwordx2 s[0:1], s[84:85], 0x68
	s_waitcnt lgkmcnt(0)
	global_load_dword v0, v0, s[0:1]
	s_waitcnt vmcnt(0)
	v_max_f32_e64 v0, |v0|, |v1|
	v_cmp_gt_f32_e32 vcc, 0x3fd9999a, v0
	s_nop 1
	s_cmp_eq_u64 vcc, exec
	s_cselect_b32 s32, 1, 0
	v_mov_b32_e32 v1, 0x21800
	v_lshl_add_u32 v0, v230, 2, v1
	ds_write_b32 v0, v241
	s_waitcnt lgkmcnt(0)
	s_mov_b64 s[0:1], exec
	s_and_b64 exec, exec, s[6:7]
	s_cbranch_execz .Ltk_setup
	global_atomic_add v241, v113, v235, s[18:19] offset:256 sc0
.Ltk_setup:
	s_mov_b64 exec, s[0:1]
	s_branch .LBB0_1077

; __global__ void __launch_bounds__(NWAVES * 64, 2) mega_fwd(Args args_) {
;     ...
;                   if (tid == 0) MISC[0] = atomicAdd(qctr, 1u);
;                   __syncthreads(); const int u = __builtin_amdgcn_readfirstlane((int)MISC[0]); __syncthreads();
.LBB0_1077:
	s_and_saveexec_b64 s[0:1], s[6:7]
	s_cbranch_execz .LBB0_1079
	v_mov_b32_e32 v1, s97
	s_waitcnt vmcnt(0) lgkmcnt(0)
	ds_write_b32 v1, v241

; #define SBAR() __builtin_amdgcn_sched_barrier(0)
;   #define PKW(P,B) cvtpk_s(P[B],P[B+1])
;     ...
;   { float sacc=pB0[0]+pB0[1]; _Pragma("unroll") for(int r=2;r<16;++r)sacc+=pB0[r]; _Pragma("unroll") for(int r=0;r<16;++r)sacc+=pB1[r]; l_reg+=sacc;
;     pw0=(u32x4){PKW(pB0,0),PKW(pB0,2),PKW(pB0,4),PKW(pB0,6)};pw1=(u32x4){PKW(pB0,8),PKW(pB0,10),PKW(pB0,12),PKW(pB0,14)};pw2=(u32x4){PKW(pB1,0),PKW(pB1,2),PKW(pB1,4),PKW(pB1,6)};pw3=(u32x4){PKW(pB1,8),PKW(pB1,10),PKW(pB1,12),PKW(pB1,14)};
;     SBAR(); pv(o,vb0+sl_cur,PAF(0),PAF(1),PAF(2),PAF(3)); }
;     ...
;   {auto rr=__builtin_amdgcn_permlane32_swap(__float_as_uint(l_reg),__float_as_uint(l_reg),false,false);l_reg=__uint_as_float(rr[0])+__uint_as_float(rr[1]);}
;   if(MODE==2)l_reg+=__builtin_amdgcn_exp2f(sinkl2-mhat);
;   if(MODE==3){ const int p_=wid*QBLK+r32; if(hi==0&&p_<len)stat[p_]=mhat+__builtin_amdgcn_logf(l_reg); }
;   if(hi==0)wsf[32+r32]=l_reg;asm volatile("s_waitcnt lgkmcnt(0)":::"memory");
.LBB0_1103:
	v_add_f32_e32 v64, v48, v49
	v_add_f32_e32 v64, v50, v64
	v_add_f32_e32 v64, v51, v64
	v_add_f32_e32 v64, v52, v64
	v_add_f32_e32 v64, v53, v64
	v_add_f32_e32 v64, v54, v64
	v_add_f32_e32 v64, v55, v64
	v_add_f32_e32 v64, v56, v64
	v_add_f32_e32 v64, v57, v64
	v_add_f32_e32 v64, v58, v64
	v_add_f32_e32 v64, v59, v64
	v_add_f32_e32 v64, v60, v64
	v_add_f32_e32 v64, v61, v64
	v_add_f32_e32 v64, v62, v64
	v_add_f32_e32 v64, v63, v64
	v_add_f32_e32 v64, v32, v64
	v_add_f32_e32 v64, v33, v64
	v_add_f32_e32 v64, v34, v64
	v_add_f32_e32 v64, v35, v64
	v_add_f32_e32 v64, v36, v64
	v_add_f32_e32 v64, v37, v64
	v_add_f32_e32 v64, v38, v64
	v_add_f32_e32 v64, v39, v64
	v_add_f32_e32 v64, v40, v64
	v_add_f32_e32 v64, v41, v64
	v_add_f32_e32 v64, v42, v64
	v_add_f32_e32 v64, v43, v64
	v_add_f32_e32 v64, v44, v64
	v_add_f32_e32 v64, v45, v64
	s_cmp_lg_u32 0, -1
	v_add_f32_e32 v64, v46, v64
	s_cselect_b32 s0, 0, 0
	v_add_f32_e32 v64, v47, v64
	s_addk_i32 s0, 0x6000
	v_add_f32_e32 v64, v80, v64
	v_cvt_pk_bf16_f32 v32, v32, v33
	v_add3_u32 v65, v237, s0, v252
	v_cvt_pk_bf16_f32 v48, v48, v49
	v_cvt_pk_bf16_f32 v49, v50, v51
	v_cvt_pk_bf16_f32 v50, v52, v53
	v_cvt_pk_bf16_f32 v51, v54, v55
	v_cvt_pk_bf16_f32 v52, v56, v57
	v_cvt_pk_bf16_f32 v53, v58, v59
	v_cvt_pk_bf16_f32 v54, v60, v61
	v_cvt_pk_bf16_f32 v55, v62, v63
	v_cvt_pk_bf16_f32 v33, v34, v35
	v_cvt_pk_bf16_f32 v34, v36, v37
	v_cvt_pk_bf16_f32 v35, v38, v39
	v_cvt_pk_bf16_f32 v36, v40, v41
	v_cvt_pk_bf16_f32 v37, v42, v43
	v_cvt_pk_bf16_f32 v38, v44, v45
	v_cvt_pk_bf16_f32 v39, v46, v47
	v_add3_u32 v65, v65, v253, s31
	ds_read_b64_tr_b16 v[40:41],v65 offset:0
	ds_read_b64_tr_b16 v[42:43],v65 offset:512
	ds_read_b64_tr_b16 v[44:45],v65 offset:1024
	ds_read_b64_tr_b16 v[46:47],v65 offset:1536
	ds_read_b64_tr_b16 v[56:57],v65 offset:2048
	ds_read_b64_tr_b16 v[58:59],v65 offset:2560
	ds_read_b64_tr_b16 v[60:61],v65 offset:3072
	ds_read_b64_tr_b16 v[62:63],v65 offset:3584
	s_waitcnt lgkmcnt(0)
	s_nop 0
	v_mfma_f32_32x32x16_bf16 v[16:31], v[48:51], v[40:43], v[16:31]
	ds_read_b64_tr_b16 v[40:41],v65 offset:4096
	ds_read_b64_tr_b16 v[42:43],v65 offset:4608
	v_mfma_f32_32x32x16_bf16 v[16:31], v[52:55], v[44:47], v[16:31]
	ds_read_b64_tr_b16 v[44:45],v65 offset:5120
	ds_read_b64_tr_b16 v[46:47],v65 offset:5632
	v_mfma_f32_32x32x16_bf16 v[16:31], v[32:35], v[56:59], v[16:31]
	ds_read_b64_tr_b16 v[56:57],v65 offset:6144
	ds_read_b64_tr_b16 v[58:59],v65 offset:6656
	v_mfma_f32_32x32x16_bf16 v[16:31], v[36:39], v[60:63], v[16:31]
	ds_read_b64_tr_b16 v[60:61],v65 offset:7168
	ds_read_b64_tr_b16 v[62:63],v65 offset:7680
	s_waitcnt lgkmcnt(0)
	v_mfma_f32_32x32x16_bf16 v[0:15], v[48:51], v[40:43], v[0:15]
	v_cmp_gt_u32_e32 vcc, 32, v247
	v_mfma_f32_32x32x16_bf16 v[0:15], v[52:55], v[44:47], v[0:15]
	v_mfma_f32_32x32x16_bf16 v[0:15], v[32:35], v[56:59], v[0:15]
	v_mov_b32_e32 v32, v64
	s_nop 1
	v_permlane32_swap_b32_e32 v64, v32
	v_mfma_f32_32x32x16_bf16 v[0:15], v[36:39], v[60:63], v[0:15]
	s_mov_b64 s[8:9], exec
	s_and_b64 exec, exec, s[6:7]
	s_cbranch_execz .Ltk_swa
	global_atomic_add v241, v113, v235, s[18:19] offset:256 sc0
.Ltk_swa:
	s_mov_b64 exec, s[8:9]
	s_and_saveexec_b64 s[0:1], vcc
	s_cbranch_execz .LBB0_1105
	s_mov_b32 s2, 0x3fb8aa3b
	v_fma_f32 v33, v251, s2, -v242
	v_exp_f32_e32 v33, v33
	v_add_f32_e32 v32, v64, v32
	v_add_f32_e32 v32, v33, v32
	ds_write_b32 v244, v32 offset:49280

; #define SBAR() __builtin_amdgcn_sched_barrier(0)
;   #define PKW(P,B) cvtpk_s(P[B],P[B+1])
;     ...
;   { float sacc=pB0[0]+pB0[1]; _Pragma("unroll") for(int r=2;r<16;++r)sacc+=pB0[r]; _Pragma("unroll") for(int r=0;r<16;++r)sacc+=pB1[r]; l_reg+=sacc;
;     pw0=(u32x4){PKW(pB0,0),PKW(pB0,2),PKW(pB0,4),PKW(pB0,6)};pw1=(u32x4){PKW(pB0,8),PKW(pB0,10),PKW(pB0,12),PKW(pB0,14)};pw2=(u32x4){PKW(pB1,0),PKW(pB1,2),PKW(pB1,4),PKW(pB1,6)};pw3=(u32x4){PKW(pB1,8),PKW(pB1,10),PKW(pB1,12),PKW(pB1,14)};
;     SBAR(); pv(o,vb0+sl_cur,PAF(0),PAF(1),PAF(2),PAF(3)); }
;     ...
;   {auto rr=__builtin_amdgcn_permlane32_swap(__float_as_uint(l_reg),__float_as_uint(l_reg),false,false);l_reg=__uint_as_float(rr[0])+__uint_as_float(rr[1]);}
;   if(MODE==2)l_reg+=__builtin_amdgcn_exp2f(sinkl2-mhat);
;   if(MODE==3){ const int p_=wid*QBLK+r32; if(hi==0&&p_<len)stat[p_]=mhat+__builtin_amdgcn_logf(l_reg); }
.LBB0_1190:
	v_add_f32_e32 v50, v80, v81
	v_add_f32_e32 v50, v82, v50
	v_add_f32_e32 v50, v83, v50
	v_add_f32_e32 v50, v84, v50
	v_add_f32_e32 v50, v85, v50
	v_add_f32_e32 v50, v86, v50
	v_add_f32_e32 v50, v87, v50
	v_add_f32_e32 v50, v88, v50
	v_add_f32_e32 v50, v89, v50
	v_add_f32_e32 v50, v90, v50
	v_add_f32_e32 v50, v91, v50
	v_add_f32_e32 v50, v92, v50
	v_add_f32_e32 v50, v93, v50
	v_add_f32_e32 v50, v94, v50
	v_add_f32_e32 v50, v95, v50
	v_add_f32_e32 v50, v0, v50
	v_add_f32_e32 v50, v1, v50
	v_add_f32_e32 v50, v2, v50
	v_add_f32_e32 v50, v3, v50
	v_add_f32_e32 v50, v4, v50
	v_add_f32_e32 v50, v5, v50
	v_add_f32_e32 v50, v6, v50
	v_add_f32_e32 v50, v7, v50
	v_add_f32_e32 v50, v8, v50
	v_add_f32_e32 v50, v9, v50
	v_add_f32_e32 v50, v10, v50
	v_add_f32_e32 v50, v11, v50
	v_add_f32_e32 v50, v12, v50
	s_cmp_lg_u32 0, -1
	v_add_f32_e32 v50, v13, v50
	s_cselect_b32 s0, 0, 0
	v_add_f32_e32 v50, v14, v50
	s_addk_i32 s0, 0x6000
	v_add_f32_e32 v50, v15, v50
	v_cvt_pk_bf16_f32 v0, v0, v1
	v_add3_u32 v49, v195, s0, v183
	v_add_f32_e32 v66, v112, v50
	v_cvt_pk_bf16_f32 v50, v80, v81
	v_cvt_pk_bf16_f32 v51, v82, v83
	v_cvt_pk_bf16_f32 v52, v84, v85
	v_cvt_pk_bf16_f32 v53, v86, v87
	v_cvt_pk_bf16_f32 v54, v88, v89
	v_cvt_pk_bf16_f32 v55, v90, v91
	v_cvt_pk_bf16_f32 v56, v92, v93
	v_cvt_pk_bf16_f32 v57, v94, v95
	v_cvt_pk_bf16_f32 v1, v2, v3
	v_cvt_pk_bf16_f32 v2, v4, v5
	v_cvt_pk_bf16_f32 v3, v6, v7
	v_cvt_pk_bf16_f32 v4, v8, v9
	v_cvt_pk_bf16_f32 v5, v10, v11
	v_cvt_pk_bf16_f32 v6, v12, v13
	v_cvt_pk_bf16_f32 v7, v14, v15
	v_add3_u32 v49, v49, v194, s12
	ds_read_b64_tr_b16 v[8:9],v49 offset:0
	ds_read_b64_tr_b16 v[10:11],v49 offset:512
	ds_read_b64_tr_b16 v[12:13],v49 offset:1024
	ds_read_b64_tr_b16 v[14:15],v49 offset:1536
	ds_read_b64_tr_b16 v[58:59],v49 offset:2048
	ds_read_b64_tr_b16 v[60:61],v49 offset:2560
	ds_read_b64_tr_b16 v[62:63],v49 offset:3072
	ds_read_b64_tr_b16 v[64:65],v49 offset:3584
	s_waitcnt lgkmcnt(0)
	s_nop 0
	v_mfma_f32_32x32x16_bf16 v[32:47], v[50:53], v[8:11], v[32:47]
	ds_read_b64_tr_b16 v[8:9],v49 offset:4096
	ds_read_b64_tr_b16 v[10:11],v49 offset:4608
	v_mfma_f32_32x32x16_bf16 v[32:47], v[54:57], v[12:15], v[32:47]
	ds_read_b64_tr_b16 v[12:13],v49 offset:5120
	ds_read_b64_tr_b16 v[14:15],v49 offset:5632
	v_mfma_f32_32x32x16_bf16 v[32:47], v[0:3], v[58:61], v[32:47]
	ds_read_b64_tr_b16 v[58:59],v49 offset:6144
	ds_read_b64_tr_b16 v[60:61],v49 offset:6656
	v_mfma_f32_32x32x16_bf16 v[32:47], v[4:7], v[62:65], v[32:47]
	ds_read_b64_tr_b16 v[62:63],v49 offset:7168
	ds_read_b64_tr_b16 v[64:65],v49 offset:7680
	s_waitcnt lgkmcnt(0)
	v_mfma_f32_32x32x16_bf16 v[16:31], v[50:53], v[8:11], v[16:31]
	v_cmp_gt_u32_e32 vcc, 32, v189
	v_cmp_lt_i32_e64 s[8:9], v182, v188
	s_and_b64 s[2:3], vcc, s[8:9]
	v_mfma_f32_32x32x16_bf16 v[16:31], v[54:57], v[12:15], v[16:31]
	v_mfma_f32_32x32x16_bf16 v[16:31], v[0:3], v[58:61], v[16:31]
	v_mov_b32_e32 v0, v66
	s_nop 1
	v_permlane32_swap_b32_e32 v66, v0
	v_add_f32_e32 v0, v66, v0
	v_mfma_f32_32x32x16_bf16 v[16:31], v[4:7], v[62:65], v[16:31]
	s_mov_b64 s[12:13], exec
	s_and_b64 exec, exec, s[6:7]
	s_cbranch_execz .Ltk_moba
	global_atomic_add v241, v113, v235, s[18:19] offset:256 sc0
.Ltk_moba:
	s_mov_b64 exec, s[12:13]
	s_and_saveexec_b64 s[0:1], s[2:3]
	s_cbranch_execz .LBB0_1192
	s_lshl_b64 s[2:3], s[20:21], 18
	s_add_u32 s5, s56, s2
	v_log_f32_e32 v1, v0
	s_addc_u32 s8, s57, s3
	s_lshl_b64 s[2:3], s[28:29], 2
	s_add_u32 s2, s5, s2
	s_addc_u32 s3, s8, s3
	v_ashrrev_i32_e32 v183, 31, v182
	v_add_f32_e32 v1, v193, v1
	v_lshl_add_u64 v[2:3], v[182:183], 2, s[2:3]
	flat_store_dword v[2:3], v1

;     ...
;   {auto rr=__builtin_amdgcn_permlane32_swap(__float_as_uint(l_reg),__float_as_uint(l_reg),false,false);l_reg=__uint_as_float(rr[0])+__uint_as_float(rr[1]);}
;   if(MODE==2)l_reg+=__builtin_amdgcn_exp2f(sinkl2-mhat);
;   if(MODE==3){ const int p_=wid*QBLK+r32; if(hi==0&&p_<len)stat[p_]=mhat+__builtin_amdgcn_logf(l_reg); }
;   if(hi==0)wsf[32+r32]=l_reg;asm volatile("s_waitcnt lgkmcnt(0)":::"memory");
; __global__ void __launch_bounds__(NWAVES * 64, 2) mega_fwd(Args args_) {
;     ...
;                   if (tid == 0) MISC[0] = atomicAdd(qctr, 1u);
.Lue_a:
	s_mov_b64 s[2:3], exec
	s_and_b64 exec, exec, s[6:7]
	s_cbranch_execz .Ltk_diff
	global_atomic_add v241, v113, v235, s[18:19] offset:256 sc0
.Ltk_diff:
	s_mov_b64 exec, s[2:3]
	s_and_saveexec_b64 s[0:1], vcc
	s_cbranch_execz .LBB0_1074
	v_add_f32_e32 v32, v65, v32
	s_bitcmp1_b32 s32, 0
	s_cbranch_scc0 .Lue_b
	s_bitcmp1_b32 s32, 8
	s_cbranch_scc1 .Lue_c
	global_store_dword v226, v32, s[16:17]
	s_nop 1

; __device__ __forceinline__ void xcd_barrier(const XcdBarrier& b) {
;     asm volatile("s_waitcnt vmcnt(0)" ::: "memory");
;     __syncthreads();
;     if (threadIdx.x == 0) {
;         unsigned* bar = b.bar;
;         __builtin_amdgcn_s_waitcnt(0);
;         unsigned nloc = b.st[0], nx = b.st[1];
;         if (nloc == 0u) { xcd_barrier_complete(bar, b.x, nloc, nx); b.st[0] = nloc; b.st[1] = nx; }
.LBB0_1302:
	s_waitcnt vmcnt(0)
	v_mov_b32_e32 v1, 0x21800
	v_lshl_add_u32 v0, v230, 2, v1
	ds_read_b32 v241, v0
	s_waitcnt lgkmcnt(0)
	s_mov_b64 s[2:3], s[84:85]
	s_getreg_b32 s4, hwreg(HW_REG_XCC_ID, 0, 4)
	s_waitcnt vmcnt(0)
	s_waitcnt lgkmcnt(0)
	s_barrier
	s_mov_b64 s[0:1], exec
	v_readlane_b32 s6, v254, 1
	v_readlane_b32 s7, v254, 2
	s_and_b64 s[6:7], s[0:1], s[6:7]
	v_mov_b64_e32 v[232:233], 0x580
	v_mov_b64_e32 v[242:243], 0x57f
	v_mov_b32_e32 v234, 0x1000
	v_mov_b32_e32 v237, 0x2000
	s_mov_b64 exec, s[6:7]
	s_cbranch_execz .LBB0_1354
	v_readlane_b32 s5, v254, 27
	s_load_dwordx2 s[2:3], s[2:3], 0xe0
	s_waitcnt vmcnt(0) expcnt(0) lgkmcnt(0)
	v_mov_b32_e32 v0, s5
	ds_read_b32 v2, v0
	v_readlane_b32 s5, v254, 28
	s_and_b32 s24, s4, 15
	s_waitcnt lgkmcnt(0)
	v_cmp_ne_u32_e32 vcc, 0, v2
	v_mov_b32_e32 v0, s5
	ds_read_b32 v0, v0
	s_cbranch_vccnz .LBB0_1318
	s_add_u32 s4, s2, 0x80200
	s_addc_u32 s5, s3, 0
	s_add_u32 s6, s2, 0x80400
	s_addc_u32 s7, s3, 0
	s_add_u32 s8, s2, 0x80500
	s_addc_u32 s9, s3, 0
	s_add_u32 s10, s2, 0x80600
	s_addc_u32 s11, s3, 0
	s_add_u32 s12, s2, 0x80700
	s_addc_u32 s13, s3, 0
	s_add_u32 s14, s2, 0x80800
	s_addc_u32 s15, s3, 0
	s_add_u32 s16, s2, 0x80900
	s_addc_u32 s17, s3, 0
	s_add_u32 s18, s2, 0x80a00
	s_addc_u32 s19, s3, 0
	s_add_u32 s20, s2, 0x80b00
	s_addc_u32 s21, s3, 0
	s_add_u32 s22, s2, 0x80c00
	s_addc_u32 s23, s3, 0
	s_add_u32 s28, s2, 0x80d00
	s_addc_u32 s29, s3, 0
	s_add_u32 s30, s2, 0x80e00
	s_addc_u32 s31, s3, 0
	s_add_u32 s34, s2, 0x80f00
	s_addc_u32 s35, s3, 0
	s_add_u32 s36, s2, 0x81000
	s_addc_u32 s37, s3, 0
	s_add_u32 s38, s2, 0x81100
	s_addc_u32 s39, s3, 0
	s_add_u32 s42, s2, 0x81200
	s_addc_u32 s43, s3, 0
	s_add_u32 s44, s2, 0x81300
	s_addc_u32 s45, s3, 0
	s_mov_b32 s25, 1
	s_branch .LBB0_1306
